# LDS-DMA staging (3-stage, XOR-swizzled) for FFN gate/up and even in-projection GEMMs + XCD tile remap
# speedup vs baseline: 1.0156x; 1.0052x over previous
; DI int tid_l() { int t = threadIdx.x; asm volatile("" : "+v"(t)); return t; }
; DI int bid_l() { int t = blockIdx.x; asm volatile("" : "+s"(t)); return t; }
; template <int MF, int BK, class Epi>
; DI void gemm_phase_t(char* lds, const GemmDesc g, const Epi epi) {
;   constexpr int BM = MF * 64, LS = BK + 8, CPR = BK / 8, RSTEP = 256 / CPR;
;   constexpr int APT = BM * CPR / 256, BPT = 128 * CPR / 256, STG = (BM + 128) * LS, NKK = BK / 16;
;   u16* sbase = (u16*)lds;
;   const int tid = tid_l(), lane = tid & 63, w = tid >> 6, wm = w >> 1, wn = w & 1, l31 = lane & 31, h = lane >> 5;
;   const int ntn = g.Npad / 128, ntm = g.M / BM, ntiles = ntm * ntn, nk = g.K / BK;
;   const int lr = tid / CPR, lc = tid % CPR;
;   for (int t = bid_l(); t < ntiles; t += gridDim.x) {
;     const int tn = t % ntn, tm = t / ntn;
;     const int m0 = tm * BM, n0 = tn * 128;
;     const u16* Ap = g.A + (size_t)(m0 + lr) * g.lda + lc * 8;
;     const u16* Bp = g.Bt + (size_t)(n0 + lr) * g.ldb + lc * 8;
.LBB0_284:
	s_andn2_b64 vcc, exec, s[2:3]
	s_mov_b64 s[2:3], 0
	v_writelane_b32 v253, s2, 39
	s_mov_b64 s[0:1], 0
	s_nop 0
	v_writelane_b32 v253, s3, 40
	s_cbranch_vccnz .LBB0_291
	v_readlane_b32 s2, v253, 41
	s_lshr_b32 s6, s2, 8
	v_mov_b32_e32 v4, v0
	s_mul_i32 s6, s6, 44
	v_readlane_b32 s7, v251, 0
	v_mov_b32_e32 v203, 0x42800000
	v_mov_b32_e32 v208, 0x13004
	v_mov_b32_e32 v214, 0x13000
	v_mov_b32_e32 v177, 0x12090
	s_cmp_ge_i32 s7, s6
	s_cbranch_scc1 .LBB0_290
	v_ashrrev_i32_e32 v2, 31, v4
	v_lshrrev_b32_e32 v2, 30, v2
	s_add_u32 s2, s30, 0x37ac000
	v_add_u32_e32 v5, v4, v2
	s_addc_u32 s3, s31, 0
	v_ashrrev_i32_e32 v2, 2, v5
	v_and_b32_e32 v5, -4, v5
	s_and_b64 s[4:5], s[20:21], exec
	v_sub_u32_e32 v5, v4, v5
	s_cselect_b32 s4, 0, 0x1c364000
	v_lshlrev_b32_e32 v6, 3, v5
	s_add_u32 s4, s30, s4
	v_ashrrev_i32_e32 v7, 31, v6
	s_addc_u32 s5, s31, 0
	v_lshlrev_b64 v[6:7], 1, v[6:7]
	s_waitcnt vmcnt(9)
	v_bfe_u32 v8, v0, 4, 2
	v_lshlrev_b32_e32 v8, 4, v8
	v_lshl_add_u64 v[160:161], s[4:5], 0, v[6:7]
	v_xor_b32_e32 v160, v160, v8
	s_mov_b64 s[4:5], 0x164c000
	v_and_b32_e32 v170, 64, v4
	v_lshl_add_u64 v[156:157], s[30:31], 0, v[6:7]
	v_xor_b32_e32 v156, v156, v8
	s_waitcnt vmcnt(8)
	v_lshl_add_u64 v[162:163], v[160:161], 0, s[4:5]
	v_and_b32_e32 v6, 0x5f, v4
	v_lshrrev_b32_e32 v7, 1, v4
	v_and_b32_e32 v172, 0xffffff9f, v4
	v_or_b32_e32 v4, 0x60, v4
	s_movk_i32 s4, 0x50
	s_mov_b64 s[8:9], 0x147ac000
	v_lshlrev_b32_e32 v5, 4, v5
	v_and_b32_e32 v171, 16, v7
	v_mul_lo_u32 v4, v4, s4
	v_mul_lo_u32 v7, v2, s4
	v_mul_lo_u32 v8, v172, s4
	v_mul_u32_u24_e32 v6, 0x50, v6
	v_lshl_add_u64 v[158:159], v[156:157], 0, s[8:9]
	v_bfe_u32 v4, v0, 2, 2
	v_bfe_u32 v5, v0, 5, 1
	v_xor_b32_e32 v4, v4, v5
	v_lshlrev_b32_e32 v4, 4, v4
	v_lshrrev_b32_e32 v5, 6, v0
	v_lshlrev_b32_e32 v5, 10, v5
	v_sub_u32_e32 v4, v4, v5
	v_lshl_add_u32 v175, v172, 6, v4
	v_xor_b32_e32 v176, 32, v175
	v_and_b32_e32 v6, 0x5f, v0
	v_lshl_add_u32 v174, v6, 6, v4
	v_add_u32_e32 v174, 0x4000, v174
	v_xor_b32_e32 v173, 32, v174
	v_readfirstlane_b32 s98, v5
	s_add_u32 s98, s98, 0x100
	s_add_u32 s99, s98, 0x6000
	s_add_u32 s100, s98, 0xc000
; DI int bid_l() { int t = blockIdx.x; asm volatile("" : "+s"(t)); return t; }
; DI f32x16 zero16() { f32x16 z; for (int i = 0; i < 16; ++i) z[i] = 0.f; return z; }
; template <int MF, int BK, class Epi>
; DI void gemm_phase_t(char* lds, const GemmDesc g, const Epi epi) {
;     ...
;   for (int t = bid_l(); t < ntiles; t += gridDim.x) {
;     const int tn = t % ntn, tm = t / ntn;
;     const int m0 = tm * BM, n0 = tn * 128;
;     const u16* Ap = g.A + (size_t)(m0 + lr) * g.lda + lc * 8;
;     const u16* Bp = g.Bt + (size_t)(n0 + lr) * g.ldb + lc * 8;
;     u32x4 ra[APT], rb[BPT];
; #pragma unroll
;     for (int j = 0; j < APT; ++j) ra[j] = *(const u32x4*)(Ap + (size_t)j * RSTEP * g.lda);
; #pragma unroll
;     for (int j = 0; j < BPT; ++j) rb[j] = *(const u32x4*)(Bp + (size_t)j * RSTEP * g.ldb);
; #pragma unroll
;     for (int j = 0; j < APT; ++j) *(u32x4*)(sbase + (lr + RSTEP * j) * LS + lc * 8) = ra[j];
; #pragma unroll
;     for (int j = 0; j < BPT; ++j) *(u32x4*)(sbase + BM * LS + (lr + RSTEP * j) * LS + lc * 8) = rb[j];
;     if (nk > 1) {
; #pragma unroll
;       for (int j = 0; j < APT; ++j) ra[j] = *(const u32x4*)(Ap + (size_t)j * RSTEP * g.lda + BK);
; #pragma unroll
;       for (int j = 0; j < BPT; ++j) rb[j] = *(const u32x4*)(Bp + (size_t)j * RSTEP * g.ldb + BK);
;     }
;     f32x16 acc[MF][2];
; #pragma unroll
;     for (int i = 0; i < MF; ++i)
; #pragma unroll
;       for (int j = 0; j < 2; ++j) acc[i][j] = zero16();
.LBB0_287:
	s_mul_hi_i32 s4, s7, 0x2e8ba2e9
	s_lshr_b32 s5, s4, 31
	s_ashr_i32 s4, s4, 3
	s_add_i32 s4, s4, s5
	s_lshl_b32 s8, s4, 8
	v_add_u32_e32 v4, s8, v2
	s_mul_i32 s5, s4, 44
	v_ashrrev_i32_e32 v5, 31, v4
	s_sub_i32 s5, s7, s5
	v_lshlrev_b64 v[68:69], 11, v[4:5]
	s_lshl_b32 s9, s5, 7
	v_lshl_add_u64 v[70:71], v[158:159], 0, v[68:69]
	s_mov_b32 s5, 0x20000
	v_add_co_u32_e32 v74, vcc, s5, v70
	s_mov_b32 s4, 0x40000
	s_nop 0
	v_addc_co_u32_e32 v75, vcc, 0, v71, vcc
	v_add_u32_e32 v4, s9, v2
	v_add_co_u32_e32 v76, vcc, s4, v70
	v_ashrrev_i32_e32 v5, 31, v4
	s_nop 0
	v_addc_co_u32_e32 v77, vcc, 0, v71, vcc
	s_mov_b32 s4, 0x60000
	v_lshlrev_b64 v[72:73], 11, v[4:5]
	v_add_co_u32_e32 v78, vcc, s4, v70
	v_lshl_add_u64 v[80:81], v[162:163], 0, v[72:73]
	s_nop 0
	v_addc_co_u32_e32 v79, vcc, 0, v71, vcc
	v_add_co_u32_e32 v82, vcc, s5, v80
	v_addc_co_u32_e32 v83, vcc, 0, v81, vcc
	s_mov_b32 m0, s98
	s_nop 0
	global_load_lds_dwordx4 v[70:71], off
	s_add_i32 m0, s98, 0x1000
	s_nop 0
	global_load_lds_dwordx4 v[74:75], off
	s_add_i32 m0, s98, 0x2000
	s_nop 0
	global_load_lds_dwordx4 v[76:77], off
	s_add_i32 m0, s98, 0x3000
	s_nop 0
	global_load_lds_dwordx4 v[78:79], off
	s_add_i32 m0, s98, 0x4000
	s_nop 0
	global_load_lds_dwordx4 v[80:81], off
	s_add_i32 m0, s98, 0x5000
	s_nop 0
	global_load_lds_dwordx4 v[82:83], off
	s_add_i32 m0, s99, 0xffffffc0
	s_nop 0
	global_load_lds_dwordx4 v[70:71], off offset:64
	s_add_i32 m0, s99, 0xfc0
	s_nop 0
	global_load_lds_dwordx4 v[74:75], off offset:64
	s_add_i32 m0, s99, 0x1fc0
	s_nop 0
	global_load_lds_dwordx4 v[76:77], off offset:64
	s_add_i32 m0, s99, 0x2fc0
	s_nop 0
	global_load_lds_dwordx4 v[78:79], off offset:64
	s_add_i32 m0, s99, 0x3fc0
	s_nop 0
	global_load_lds_dwordx4 v[80:81], off offset:64
	s_add_i32 m0, s99, 0x4fc0
	s_nop 0
	global_load_lds_dwordx4 v[82:83], off offset:64
	v_mov_b32_e32 v4, 0
	s_mov_b64 s[4:5], 0
	v_mov_b32_e32 v5, v4
	v_mov_b32_e32 v6, v4
	v_mov_b32_e32 v7, v4
	v_mov_b32_e32 v8, v4
	v_mov_b32_e32 v9, v4
	v_mov_b32_e32 v10, v4
	v_mov_b32_e32 v11, v4
	v_mov_b32_e32 v12, v4
	v_mov_b32_e32 v13, v4
	v_mov_b32_e32 v14, v4
	v_mov_b32_e32 v15, v4
	v_mov_b32_e32 v16, v4
	v_mov_b32_e32 v17, v4
	v_mov_b32_e32 v18, v4
	v_mov_b32_e32 v19, v4
	v_mov_b32_e32 v20, v4
	v_mov_b32_e32 v21, v4
	v_mov_b32_e32 v22, v4
	v_mov_b32_e32 v23, v4
	v_mov_b32_e32 v24, v4
	v_mov_b32_e32 v25, v4
	v_mov_b32_e32 v26, v4
	v_mov_b32_e32 v27, v4
	v_mov_b32_e32 v28, v4
	v_mov_b32_e32 v29, v4
	v_mov_b32_e32 v30, v4
	v_mov_b32_e32 v31, v4
	v_mov_b32_e32 v32, v4
	v_mov_b32_e32 v33, v4
	v_mov_b32_e32 v34, v4
	v_mov_b32_e32 v35, v4
	v_mov_b32_e32 v36, v4
	v_mov_b32_e32 v37, v4
	v_mov_b32_e32 v38, v4
	v_mov_b32_e32 v39, v4
	v_mov_b32_e32 v40, v4
	v_mov_b32_e32 v41, v4
	v_mov_b32_e32 v42, v4
	v_lshl_add_u64 v[164:165], v[156:157], 0, v[68:69]
	v_lshl_add_u64 v[168:169], v[160:161], 0, v[72:73]
	v_mov_b32_e32 v43, v4
	v_mov_b32_e32 v68, v4
	v_mov_b32_e32 v69, v4
	v_mov_b32_e32 v70, v4
	v_mov_b32_e32 v71, v4
	v_mov_b32_e32 v72, v4
	v_mov_b32_e32 v44, v4
	v_mov_b32_e32 v45, v4
	v_mov_b32_e32 v46, v4
	v_mov_b32_e32 v47, v4
	v_mov_b32_e32 v48, v4
	v_mov_b32_e32 v49, v4
	v_mov_b32_e32 v50, v4
	v_mov_b32_e32 v51, v4
	v_mov_b32_e32 v52, v4
	v_mov_b32_e32 v53, v4
	v_mov_b32_e32 v54, v4
	v_mov_b32_e32 v55, v4
	v_mov_b32_e32 v56, v4
	v_mov_b32_e32 v57, v4
	v_mov_b32_e32 v58, v4
	v_mov_b32_e32 v59, v4
	v_mov_b32_e32 v60, v4
	v_mov_b32_e32 v61, v4
	v_mov_b32_e32 v62, v4
	v_mov_b32_e32 v63, v4
	v_mov_b32_e32 v64, v4
	v_mov_b32_e32 v65, v4
	v_mov_b32_e32 v66, v4
	v_mov_b32_e32 v67, v4
	v_mov_b32_e32 v73, v4
	v_mov_b32_e32 v74, v4
	v_mov_b32_e32 v75, v4
	v_mov_b32_e32 v76, v4
	v_mov_b32_e32 v77, v4
	v_mov_b32_e32 v78, v4
	v_mov_b32_e32 v79, v4
	v_mov_b32_e32 v80, v4
	v_mov_b32_e32 v81, v4
	v_mov_b32_e32 v82, v4
	v_mov_b32_e32 v83, v4
	v_mov_b32_e32 v84, v4
	v_mov_b32_e32 v85, v4
	v_mov_b32_e32 v86, v4
	v_mov_b32_e32 v87, v4
	v_mov_b32_e32 v88, v4
	v_mov_b32_e32 v89, v4
	v_mov_b32_e32 v90, v4
	v_mov_b32_e32 v91, v4
	v_mov_b32_e32 v92, v4
	v_mov_b32_e32 v93, v4
	v_mov_b32_e32 v94, v4
	v_mov_b32_e32 v95, v4
	v_mov_b32_e32 v96, v4
	v_mov_b32_e32 v97, v4
	v_mov_b32_e32 v98, v4
	v_mov_b32_e32 v99, v4
	v_mov_b32_e32 v100, v4
	v_mov_b32_e32 v101, v4
	v_mov_b32_e32 v102, v4
	v_mov_b32_e32 v103, v4
	v_mov_b32_e32 v104, v4
	v_mov_b32_e32 v105, v4
	v_mov_b32_e32 v106, v4
	v_mov_b32_e32 v107, v4
	v_mov_b32_e32 v108, v4
	v_mov_b32_e32 v109, v4
	v_mov_b32_e32 v110, v4
	v_mov_b32_e32 v111, v4
	v_mov_b32_e32 v112, v4
	v_mov_b32_e32 v113, v4
	v_mov_b32_e32 v114, v4
	v_mov_b32_e32 v115, v4
	v_mov_b32_e32 v116, v4
	v_mov_b32_e32 v117, v4
	v_mov_b32_e32 v118, v4
	v_mov_b32_e32 v119, v4
	v_mov_b32_e32 v120, v4
	v_mov_b32_e32 v121, v4
	v_mov_b32_e32 v122, v4
	v_mov_b32_e32 v123, v4
	v_mov_b32_e32 v124, v4
	v_mov_b32_e32 v125, v4
	v_mov_b32_e32 v126, v4
	v_mov_b32_e32 v127, v4
	v_mov_b32_e32 v128, v4
	v_mov_b32_e32 v129, v4
	v_mov_b32_e32 v130, v4
	v_mov_b32_e32 v131, v4
	s_mov_b32 s11, 0x147ac000
	s_mov_b32 s12, 0x147cc000
	s_mov_b32 s13, 0x147ec000
	s_mov_b32 s14, 0x1480c000

; DI int tid_l() { int t = threadIdx.x; asm volatile("" : "+v"(t)); return t; }
; DI int bid_l() { int t = blockIdx.x; asm volatile("" : "+s"(t)); return t; }
; template <int MF, int BK, class Epi>
; DI void gemm_phase_t(char* lds, const GemmDesc g, const Epi epi) {
;   constexpr int BM = MF * 64, LS = BK + 8, CPR = BK / 8, RSTEP = 256 / CPR;
;   constexpr int APT = BM * CPR / 256, BPT = 128 * CPR / 256, STG = (BM + 128) * LS, NKK = BK / 16;
;   u16* sbase = (u16*)lds;
;   const int tid = tid_l(), lane = tid & 63, w = tid >> 6, wm = w >> 1, wn = w & 1, l31 = lane & 31, h = lane >> 5;
;   const int ntn = g.Npad / 128, ntm = g.M / BM, ntiles = ntm * ntn, nk = g.K / BK;
;   const int lr = tid / CPR, lc = tid % CPR;
;   for (int t = bid_l(); t < ntiles; t += gridDim.x) {
;     const int tn = t % ntn, tm = t / ntn;
;     const int m0 = tm * BM, n0 = tn * 128;
;     const u16* Ap = g.A + (size_t)(m0 + lr) * g.lda + lc * 8;
;     const u16* Bp = g.Bt + (size_t)(n0 + lr) * g.ldb + lc * 8;
;     u32x4 ra[APT], rb[BPT];
; #pragma unroll
;     for (int j = 0; j < APT; ++j) ra[j] = *(const u32x4*)(Ap + (size_t)j * RSTEP * g.lda);
; #pragma unroll
;     for (int j = 0; j < BPT; ++j) rb[j] = *(const u32x4*)(Bp + (size_t)j * RSTEP * g.ldb);
; #pragma unroll
;     for (int j = 0; j < APT; ++j) *(u32x4*)(sbase + (lr + RSTEP * j) * LS + lc * 8) = ra[j];
; #pragma unroll
;     for (int j = 0; j < BPT; ++j) *(u32x4*)(sbase + BM * LS + (lr + RSTEP * j) * LS + lc * 8) = rb[j];
;     if (nk > 1) {
; #pragma unroll
;       for (int j = 0; j < APT; ++j) ra[j] = *(const u32x4*)(Ap + (size_t)j * RSTEP * g.lda + BK);
; #pragma unroll
;       for (int j = 0; j < BPT; ++j) rb[j] = *(const u32x4*)(Bp + (size_t)j * RSTEP * g.ldb + BK);
;     }
.LBB0_950:
	s_and_b64 vcc, exec, s[0:1]
	s_cbranch_vccz .LBB0_957
	v_mov_b32_e32 v4, v0
	v_readlane_b32 s10, v251, 0
	v_mov_b32_e32 v203, 0x42800000
	v_mov_b32_e32 v208, 0x13004
	v_mov_b32_e32 v214, 0x13000
	s_cmpk_gt_i32 s10, 0x10ff
	s_cbranch_scc1 .LBB0_956
	v_ashrrev_i32_e32 v2, 31, v4
	v_lshrrev_b32_e32 v2, 30, v2
	v_add_u32_e32 v5, v4, v2
	v_ashrrev_i32_e32 v2, 2, v5
	v_and_b32_e32 v5, -4, v5
	v_sub_u32_e32 v5, v4, v5
	v_lshlrev_b32_e32 v6, 3, v5
	v_ashrrev_i32_e32 v7, 31, v6
	s_waitcnt vmcnt(10)
	v_bfe_u32 v8, v0, 4, 2
	v_lshlrev_b32_e32 v8, 4, v8
	v_lshl_add_u64 v[156:157], v[6:7], 1, s[30:31]
	v_xor_b32_e32 v156, v156, v8
	s_mov_b64 s[0:1], 0x147ac000
	s_add_u32 s6, s30, 0x37ac000
	s_waitcnt vmcnt(9)
	v_lshl_add_u64 v[158:159], v[156:157], 0, s[0:1]
	s_mov_b64 s[0:1], 0xc4c000
	s_addc_u32 s7, s31, 0
	v_bfe_u32 v8, v4, 5, 1
	v_and_b32_e32 v9, 64, v4
	v_lshl_add_u64 v[160:161], v[156:157], 0, s[0:1]
	v_and_b32_e32 v6, 0x5f, v4
	v_and_b32_e32 v168, 0xffffff9f, v4
	v_or_b32_e32 v4, 0x60, v4
	s_movk_i32 s0, 0x50
	s_add_u32 s8, s30, 0xe1ac000
	v_lshlrev_b32_e32 v5, 4, v5
	v_lshlrev_b32_e32 v7, 4, v8
	v_lshl_or_b32 v169, v8, 3, v9
	v_mul_lo_u32 v4, v4, s0
	v_mul_lo_u32 v8, v2, s0
	v_mul_lo_u32 v9, v168, s0
	v_mul_u32_u24_e32 v6, 0x50, v6
	s_addc_u32 s9, s31, 0
	v_bfe_u32 v4, v0, 2, 2
	v_bfe_u32 v5, v0, 5, 1
	v_xor_b32_e32 v4, v4, v5
	v_lshlrev_b32_e32 v4, 4, v4
	v_lshrrev_b32_e32 v5, 6, v0
	v_lshlrev_b32_e32 v5, 10, v5
	v_sub_u32_e32 v4, v4, v5
	v_lshl_add_u32 v172, v168, 6, v4
	v_xor_b32_e32 v173, 32, v172
	v_and_b32_e32 v6, 0x5f, v0
	v_lshl_add_u32 v171, v6, 6, v4
	v_add_u32_e32 v171, 0x4000, v171
	v_xor_b32_e32 v170, 32, v171
	v_readfirstlane_b32 s98, v5
	s_add_u32 s98, s98, 0x100
	s_add_u32 s99, s98, 0x6000
	s_add_u32 s100, s98, 0xc000
.LBB0_953:
	s_ashr_i32 s0, s10, 31
	s_lshr_b32 s0, s0, 27
	s_add_i32 s0, s10, s0
	s_and_b32 s1, s0, 0x1ffffe0
	s_lshl_b32 s0, s0, 3
	s_and_b32 s2, s0, 0xffffff00
	v_add_u32_e32 v4, s2, v2
	v_ashrrev_i32_e32 v5, 31, v4
	s_sub_i32 s1, s10, s1
	v_lshlrev_b64 v[68:69], 11, v[4:5]
	s_lshl_b32 s3, s1, 7
	v_lshl_add_u64 v[70:71], v[158:159], 0, v[68:69]
	s_mov_b32 s1, 0x20000
	v_add_co_u32_e32 v74, vcc, s1, v70
	s_mov_b32 s0, 0x40000
	s_nop 0
	v_addc_co_u32_e32 v75, vcc, 0, v71, vcc
	v_add_u32_e32 v4, s3, v2
	v_add_co_u32_e32 v76, vcc, s0, v70
	v_ashrrev_i32_e32 v5, 31, v4
	s_nop 0
	v_addc_co_u32_e32 v77, vcc, 0, v71, vcc
	s_mov_b32 s0, 0x60000
	v_lshlrev_b64 v[72:73], 11, v[4:5]
	v_add_co_u32_e32 v78, vcc, s0, v70
	v_lshl_add_u64 v[80:81], v[160:161], 0, v[72:73]
	s_nop 0
	v_addc_co_u32_e32 v79, vcc, 0, v71, vcc
	v_add_co_u32_e32 v82, vcc, s1, v80
	v_addc_co_u32_e32 v83, vcc, 0, v81, vcc
	s_mov_b32 m0, s98
	s_nop 0
	global_load_lds_dwordx4 v[70:71], off
	s_add_i32 m0, s98, 0x1000
	s_nop 0
	global_load_lds_dwordx4 v[74:75], off
	s_add_i32 m0, s98, 0x2000
	s_nop 0
	global_load_lds_dwordx4 v[76:77], off
	s_add_i32 m0, s98, 0x3000
	s_nop 0
	global_load_lds_dwordx4 v[78:79], off
	s_add_i32 m0, s98, 0x4000
	s_nop 0
	global_load_lds_dwordx4 v[80:81], off
	s_add_i32 m0, s98, 0x5000
	s_nop 0
	global_load_lds_dwordx4 v[82:83], off
	s_add_i32 m0, s99, 0xffffffc0
	s_nop 0
	global_load_lds_dwordx4 v[70:71], off offset:64
	s_add_i32 m0, s99, 0xfc0
	s_nop 0
	global_load_lds_dwordx4 v[74:75], off offset:64
	s_add_i32 m0, s99, 0x1fc0
	s_nop 0
	global_load_lds_dwordx4 v[76:77], off offset:64
	s_add_i32 m0, s99, 0x2fc0
	s_nop 0
	global_load_lds_dwordx4 v[78:79], off offset:64
	s_add_i32 m0, s99, 0x3fc0
	s_nop 0
	global_load_lds_dwordx4 v[80:81], off offset:64
	s_add_i32 m0, s99, 0x4fc0
	s_nop 0
	global_load_lds_dwordx4 v[82:83], off offset:64
	v_mov_b32_e32 v4, 0
	s_mov_b64 s[0:1], 0
	v_mov_b32_e32 v5, v4
	v_mov_b32_e32 v6, v4
	v_mov_b32_e32 v7, v4
	v_mov_b32_e32 v8, v4
	v_mov_b32_e32 v9, v4
	v_mov_b32_e32 v10, v4
	v_mov_b32_e32 v11, v4
	v_mov_b32_e32 v12, v4
	v_mov_b32_e32 v13, v4
	v_mov_b32_e32 v14, v4
	v_mov_b32_e32 v15, v4
	v_mov_b32_e32 v16, v4
	s_waitcnt lgkmcnt(0)
	v_mov_b32_e32 v17, v4
	v_mov_b32_e32 v18, v4
	v_mov_b32_e32 v19, v4
	v_mov_b32_e32 v20, v4
	v_mov_b32_e32 v21, v4
	v_mov_b32_e32 v22, v4
	v_mov_b32_e32 v23, v4
	v_mov_b32_e32 v24, v4
	v_mov_b32_e32 v25, v4
	v_mov_b32_e32 v26, v4
	v_mov_b32_e32 v27, v4
	v_mov_b32_e32 v28, v4
	v_mov_b32_e32 v29, v4
	v_mov_b32_e32 v30, v4
	v_mov_b32_e32 v31, v4
	v_mov_b32_e32 v32, v4
	v_mov_b32_e32 v33, v4
	v_mov_b32_e32 v34, v4
	v_mov_b32_e32 v35, v4
	v_mov_b32_e32 v36, v4
	v_mov_b32_e32 v37, v4
	v_mov_b32_e32 v38, v4
	v_mov_b32_e32 v39, v4
	v_mov_b32_e32 v40, v4
	v_mov_b32_e32 v41, v4
	v_mov_b32_e32 v42, v4
	v_lshl_add_u64 v[162:163], v[156:157], 0, v[68:69]
	v_lshl_add_u64 v[164:165], v[156:157], 0, v[72:73]
	v_mov_b32_e32 v43, v4
	v_mov_b32_e32 v68, v4
	v_mov_b32_e32 v69, v4
	v_mov_b32_e32 v70, v4
	v_mov_b32_e32 v71, v4
	v_mov_b32_e32 v72, v4
	v_mov_b32_e32 v73, v4
	v_mov_b32_e32 v44, v4
	v_mov_b32_e32 v45, v4
	v_mov_b32_e32 v46, v4
	v_mov_b32_e32 v47, v4
	v_mov_b32_e32 v48, v4
	v_mov_b32_e32 v49, v4
	v_mov_b32_e32 v50, v4
	v_mov_b32_e32 v51, v4
	v_mov_b32_e32 v52, v4
	v_mov_b32_e32 v53, v4
	v_mov_b32_e32 v54, v4
	v_mov_b32_e32 v55, v4
	v_mov_b32_e32 v56, v4
	v_mov_b32_e32 v57, v4
	v_mov_b32_e32 v58, v4
	v_mov_b32_e32 v59, v4
	v_mov_b32_e32 v60, v4
	v_mov_b32_e32 v61, v4
	v_mov_b32_e32 v62, v4
	v_mov_b32_e32 v63, v4
	v_mov_b32_e32 v64, v4
	v_mov_b32_e32 v65, v4
	v_mov_b32_e32 v66, v4
	v_mov_b32_e32 v67, v4
	v_mov_b32_e32 v74, v4
	v_mov_b32_e32 v75, v4
	v_mov_b32_e32 v76, v4
	v_mov_b32_e32 v77, v4
	v_mov_b32_e32 v78, v4
	v_mov_b32_e32 v79, v4
	v_mov_b32_e32 v80, v4
	v_mov_b32_e32 v81, v4
	v_mov_b32_e32 v82, v4
	v_mov_b32_e32 v83, v4
	v_mov_b32_e32 v84, v4
	v_mov_b32_e32 v85, v4
	v_mov_b32_e32 v86, v4
	v_mov_b32_e32 v87, v4
	v_mov_b32_e32 v88, v4
	v_mov_b32_e32 v89, v4
	v_mov_b32_e32 v90, v4
	v_mov_b32_e32 v91, v4
	v_mov_b32_e32 v92, v4
	v_mov_b32_e32 v93, v4
	v_mov_b32_e32 v94, v4
	v_mov_b32_e32 v95, v4
	v_mov_b32_e32 v96, v4
	v_mov_b32_e32 v97, v4
	v_mov_b32_e32 v98, v4
	v_mov_b32_e32 v99, v4
	v_mov_b32_e32 v100, v4
	v_mov_b32_e32 v101, v4
	v_mov_b32_e32 v102, v4
	v_mov_b32_e32 v103, v4
	v_mov_b32_e32 v104, v4
	v_mov_b32_e32 v105, v4
	v_mov_b32_e32 v106, v4
	v_mov_b32_e32 v107, v4
	v_mov_b32_e32 v108, v4
	v_mov_b32_e32 v109, v4
	v_mov_b32_e32 v110, v4
	v_mov_b32_e32 v111, v4
	v_mov_b32_e32 v112, v4
	v_mov_b32_e32 v113, v4
	v_mov_b32_e32 v114, v4
	v_mov_b32_e32 v115, v4
	v_mov_b32_e32 v116, v4
	v_mov_b32_e32 v117, v4
	v_mov_b32_e32 v118, v4
	v_mov_b32_e32 v119, v4
	v_mov_b32_e32 v120, v4
	v_mov_b32_e32 v121, v4
	v_mov_b32_e32 v122, v4
	v_mov_b32_e32 v123, v4
	v_mov_b32_e32 v124, v4
	v_mov_b32_e32 v125, v4
	v_mov_b32_e32 v126, v4
	v_mov_b32_e32 v127, v4
	v_mov_b32_e32 v128, v4
	v_mov_b32_e32 v129, v4
	v_mov_b32_e32 v130, v4
	v_mov_b32_e32 v131, v4
	s_mov_b32 s5, 0x147ac000
	s_mov_b32 s11, 0x147cc000
	s_mov_b32 s12, 0x147ec000
	s_mov_b32 s13, 0x1480c000
; #define MFMA32(a, b, c) __builtin_amdgcn_mfma_f32_32x32x16_bf16((a), (b), (c), 0, 0, 0)
; template <int MF, int BK, class Epi>
; DI void gemm_phase_t(char* lds, const GemmDesc g, const Epi epi) {
;     ...
;     for (int kt = 0; kt < nk; ++kt) {
;       __syncthreads();
;       const u16* sA = sbase + (kt & 1) * STG;
;       const u16* sB = sA + BM * LS;
;       if (kt + 1 < nk) {
;         u16* nA = sbase + ((kt + 1) & 1) * STG;
; #pragma unroll
;         for (int j = 0; j < APT; ++j) *(u32x4*)(nA + (lr + RSTEP * j) * LS + lc * 8) = ra[j];
; #pragma unroll
;         for (int j = 0; j < BPT; ++j) *(u32x4*)(nA + BM * LS + (lr + RSTEP * j) * LS + lc * 8) = rb[j];
;         if (kt + 2 < nk) {
; #pragma unroll
;           for (int j = 0; j < APT; ++j) ra[j] = *(const u32x4*)(Ap + (size_t)j * RSTEP * g.lda + (kt + 2) * BK);
; #pragma unroll
;           for (int j = 0; j < BPT; ++j) rb[j] = *(const u32x4*)(Bp + (size_t)j * RSTEP * g.ldb + (kt + 2) * BK);
;         }
;       }
;       bf16x8 af[NKK][MF], bfr[NKK][2];
; #pragma unroll
;       for (int kk = 0; kk < NKK; ++kk) {
; #pragma unroll
;         for (int ni = 0; ni < 2; ++ni) bfr[kk][ni] = *(const bf16x8*)(sB + (wn * 64 + ni * 32 + l31) * LS + kk * 16 + h * 8);
; #pragma unroll
;         for (int mi = 0; mi < MF; ++mi) af[kk][mi] = *(const bf16x8*)(sA + (wm * (MF * 32) + mi * 32 + l31) * LS + kk * 16 + h * 8);
;       }
;       __builtin_amdgcn_sched_barrier(0);
; #pragma unroll
;       for (int kk = 0; kk < NKK; ++kk)
; #pragma unroll
;         for (int mi = 0; mi < MF; ++mi)
; #pragma unroll
;           for (int ni = 0; ni < 2; ++ni) acc[mi][ni] = MFMA32(bfr[kk][ni], af[kk][mi], acc[mi][ni]);
.LBB0_954:
	v_lshl_add_u64 v[182:183], v[162:163], 0, s[0:1]
	v_add_co_u32_e32 v194, vcc, s5, v182
	v_lshl_add_u64 v[190:191], v[164:165], 0, s[0:1]
	s_nop 0
	v_addc_co_u32_e32 v195, vcc, 0, v183, vcc
	v_add_co_u32_e32 v198, vcc, s11, v182
	s_mov_b32 s4, 0xc4c000
	s_nop 0
	v_addc_co_u32_e32 v199, vcc, 0, v183, vcc
	v_add_co_u32_e32 v200, vcc, s12, v182
	s_waitcnt lgkmcnt(0)
	s_nop 0
	v_addc_co_u32_e32 v201, vcc, 0, v183, vcc
	v_add_co_u32_e32 v204, vcc, s13, v182
	s_waitcnt vmcnt(6)
	s_barrier
	s_nop 0
	v_addc_co_u32_e32 v205, vcc, 0, v183, vcc
	v_add_co_u32_e32 v206, vcc, s4, v190
	s_mov_b32 s4, 0xc6c000
	s_nop 0
	v_addc_co_u32_e32 v207, vcc, 0, v191, vcc
	v_add_co_u32_e32 v246, vcc, s4, v190
	s_add_i32 m0, s100, 0xffffff80
	s_nop 0
	global_load_lds_dwordx4 v[194:195], off offset:128
	s_add_i32 m0, s100, 0xf80
	s_nop 0
	global_load_lds_dwordx4 v[198:199], off offset:128
	s_add_i32 m0, s100, 0x1f80
	s_nop 0
	global_load_lds_dwordx4 v[200:201], off offset:128
	s_add_i32 m0, s100, 0x2f80
	s_nop 0
	global_load_lds_dwordx4 v[204:205], off offset:128
	v_addc_co_u32_e32 v247, vcc, 0, v191, vcc
	s_add_i32 m0, s100, 0x3f80
	s_nop 0
	global_load_lds_dwordx4 v[206:207], off offset:128
	s_add_i32 m0, s100, 0x4f80
	s_nop 0
	global_load_lds_dwordx4 v[246:247], off offset:128
	v_add_u32_e32 v174, s98, v172
	v_add_u32_e32 v175, s98, v173
	v_add_u32_e32 v176, s98, v171
	v_add_u32_e32 v177, s98, v170
	ds_read_b128 v[132:135], v176
	ds_read_b128 v[222:225], v177
	ds_read_b128 v[136:139], v176 offset:2048
	ds_read_b128 v[226:229], v177 offset:2048
	ds_read_b128 v[140:143], v174
	ds_read_b128 v[144:147], v175
	ds_read_b128 v[148:151], v174 offset:2048
	ds_read_b128 v[152:155], v175 offset:2048
	ds_read_b128 v[230:233], v174 offset:4096
	ds_read_b128 v[234:237], v175 offset:4096
	ds_read_b128 v[238:241], v174 offset:6144
	ds_read_b128 v[242:245], v175 offset:6144
	s_waitcnt lgkmcnt(7)
	v_mfma_f32_32x32x16_bf16 v[116:131], v[132:135], v[140:143], v[116:131]
	s_waitcnt lgkmcnt(0)
	s_waitcnt vmcnt(6)
	s_barrier
	v_mfma_f32_32x32x16_bf16 v[100:115], v[136:139], v[140:143], v[100:115]
	v_mfma_f32_32x32x16_bf16 v[84:99], v[132:135], v[148:151], v[84:99]
	v_mfma_f32_32x32x16_bf16 v[68:83], v[136:139], v[148:151], v[68:83]
	v_mfma_f32_32x32x16_bf16 v[52:67], v[132:135], v[230:233], v[52:67]
	v_mfma_f32_32x32x16_bf16 v[36:51], v[136:139], v[230:233], v[36:51]
	v_mfma_f32_32x32x16_bf16 v[20:35], v[132:135], v[238:241], v[20:35]
	v_mfma_f32_32x32x16_bf16 v[4:19], v[136:139], v[238:241], v[4:19]
	s_add_i32 m0, s98, 0xffffff40
	s_nop 0
	global_load_lds_dwordx4 v[194:195], off offset:192
	s_add_i32 m0, s98, 0xf40
	s_nop 0
	global_load_lds_dwordx4 v[198:199], off offset:192
	v_mfma_f32_32x32x16_bf16 v[116:131], v[222:225], v[144:147], v[116:131]
	v_mfma_f32_32x32x16_bf16 v[100:115], v[226:229], v[144:147], v[100:115]
	v_mfma_f32_32x32x16_bf16 v[84:99], v[222:225], v[152:155], v[84:99]
	v_mfma_f32_32x32x16_bf16 v[68:83], v[226:229], v[152:155], v[68:83]
	s_add_i32 m0, s98, 0x1f40
	s_nop 0
	global_load_lds_dwordx4 v[200:201], off offset:192
	s_add_i32 m0, s98, 0x2f40
	s_nop 0
	global_load_lds_dwordx4 v[204:205], off offset:192
	s_add_i32 m0, s98, 0x3f40
	s_nop 0
	global_load_lds_dwordx4 v[206:207], off offset:192
	s_add_i32 m0, s98, 0x4f40
	s_nop 0
	global_load_lds_dwordx4 v[246:247], off offset:192
	v_add_u32_e32 v132, s99, v172
	v_add_u32_e32 v133, s99, v173
	v_add_u32_e32 v134, s99, v171
	v_add_u32_e32 v135, s99, v170
	ds_read_b128 v[174:177], v134
	ds_read_b128 v[178:181], v135
	ds_read_b128 v[182:185], v134 offset:2048
	ds_read_b128 v[186:189], v135 offset:2048
	v_mfma_f32_32x32x16_bf16 v[52:67], v[222:225], v[234:237], v[52:67]
	v_mfma_f32_32x32x16_bf16 v[36:51], v[226:229], v[234:237], v[36:51]
	v_mfma_f32_32x32x16_bf16 v[20:35], v[222:225], v[242:245], v[20:35]
	ds_read_b128 v[190:193], v132
	ds_read_b128 v[218:221], v133
	ds_read_b128 v[222:225], v132 offset:2048
	ds_read_b128 v[230:233], v133 offset:2048
	ds_read_b128 v[234:237], v132 offset:4096
	ds_read_b128 v[238:241], v133 offset:4096
	ds_read_b128 v[246:249], v132 offset:6144
	ds_read_b128 v[204:207], v133 offset:6144
	v_mfma_f32_32x32x16_bf16 v[4:19], v[226:229], v[242:245], v[4:19]
	s_waitcnt lgkmcnt(7)
	v_mfma_f32_32x32x16_bf16 v[116:131], v[174:177], v[190:193], v[116:131]
	s_add_u32 s0, s0, 0x80
	s_addc_u32 s1, s1, 0
	s_cmpk_eq_i32 s0, 0x780
	v_mfma_f32_32x32x16_bf16 v[100:115], v[182:185], v[190:193], v[100:115]
	s_waitcnt lgkmcnt(5)
	v_mfma_f32_32x32x16_bf16 v[84:99], v[174:177], v[222:225], v[84:99]
	v_mfma_f32_32x32x16_bf16 v[68:83], v[182:185], v[222:225], v[68:83]
	s_waitcnt lgkmcnt(3)
	v_mfma_f32_32x32x16_bf16 v[52:67], v[174:177], v[234:237], v[52:67]
	v_mfma_f32_32x32x16_bf16 v[36:51], v[182:185], v[234:237], v[36:51]
	s_waitcnt lgkmcnt(1)
	v_mfma_f32_32x32x16_bf16 v[20:35], v[174:177], v[246:249], v[20:35]
	v_mfma_f32_32x32x16_bf16 v[4:19], v[182:185], v[246:249], v[4:19]
	v_mfma_f32_32x32x16_bf16 v[116:131], v[178:181], v[218:221], v[116:131]
	v_mfma_f32_32x32x16_bf16 v[100:115], v[186:189], v[218:221], v[100:115]
	v_mfma_f32_32x32x16_bf16 v[84:99], v[178:181], v[230:233], v[84:99]
	v_mfma_f32_32x32x16_bf16 v[68:83], v[186:189], v[230:233], v[68:83]
	v_mfma_f32_32x32x16_bf16 v[52:67], v[178:181], v[238:241], v[52:67]
	v_mfma_f32_32x32x16_bf16 v[36:51], v[186:189], v[238:241], v[36:51]
	s_waitcnt lgkmcnt(0)
	v_mfma_f32_32x32x16_bf16 v[20:35], v[178:181], v[204:207], v[20:35]
	v_mfma_f32_32x32x16_bf16 v[4:19], v[186:189], v[204:207], v[4:19]
	s_mov_b32 s101, s100
	s_mov_b32 s100, s99
	s_mov_b32 s99, s98
	s_mov_b32 s98, s101
	s_cbranch_scc0 .LBB0_954
	s_waitcnt vmcnt(6)
	s_barrier
; #define MFMA32(a, b, c) __builtin_amdgcn_mfma_f32_32x32x16_bf16((a), (b), (c), 0, 0, 0)
; DI unsigned pack2(float a, float b) { f2_t v = {a, b}; return __builtin_bit_cast(unsigned, __builtin_convertvector(v, bf2_t)); }
; template <int MF, int BK, class Epi>
; DI void gemm_phase_t(char* lds, const GemmDesc g, const Epi epi) {
;     ...
;       for (int kk = 0; kk < NKK; ++kk) {
; #pragma unroll
;         for (int ni = 0; ni < 2; ++ni) bfr[kk][ni] = *(const bf16x8*)(sB + (wn * 64 + ni * 32 + l31) * LS + kk * 16 + h * 8);
; #pragma unroll
;         for (int mi = 0; mi < MF; ++mi) af[kk][mi] = *(const bf16x8*)(sA + (wm * (MF * 32) + mi * 32 + l31) * LS + kk * 16 + h * 8);
;       }
;       __builtin_amdgcn_sched_barrier(0);
; #pragma unroll
;       for (int kk = 0; kk < NKK; ++kk)
; #pragma unroll
;         for (int mi = 0; mi < MF; ++mi)
; #pragma unroll
;           for (int ni = 0; ni < 2; ++ni) acc[mi][ni] = MFMA32(bfr[kk][ni], af[kk][mi], acc[mi][ni]);
;   template <int MF> DI void operator()(f32x16 (&acc)[MF][2], int mb, int nb, int l31, int h) const {
; #pragma unroll
;     for (int mi = 0; mi < MF; ++mi) {
;       const int row = mb + mi * 32 + l31;
; #pragma unroll
;       for (int g4 = 0; g4 < 4; ++g4) {
;         const int col0 = nb + 16 * g4 + 8 * h;
;         u16* dst = (col0 < 2560) ? zhg + (size_t)row * 2560 + col0 : zhy + (size_t)row * 1536 + (col0 - 2560);
;         *(u32x4*)dst = (u32x4){pack2(acc[mi][0][4 * g4], acc[mi][0][4 * g4 + 1]), pack2(acc[mi][0][4 * g4 + 2], acc[mi][0][4 * g4 + 3]),
;                                pack2(acc[mi][1][4 * g4], acc[mi][1][4 * g4 + 1]), pack2(acc[mi][1][4 * g4 + 2], acc[mi][1][4 * g4 + 3])};
;       }
;     }
;   }
	v_add_u32_e32 v222, s98, v172
	v_add_u32_e32 v223, s98, v173
	v_add_u32_e32 v224, s98, v171
	v_add_u32_e32 v225, s98, v170
	ds_read_b128 v[132:135], v224
	ds_read_b128 v[136:139], v225
	ds_read_b128 v[140:143], v224 offset:2048
	ds_read_b128 v[144:147], v225 offset:2048
	ds_read_b128 v[148:151], v222
	ds_read_b128 v[152:155], v223
	ds_read_b128 v[162:165], v222 offset:2048
	ds_read_b128 v[174:177], v223 offset:2048
	ds_read_b128 v[178:181], v222 offset:4096
	ds_read_b128 v[182:185], v223 offset:4096
	ds_read_b128 v[186:189], v222 offset:6144
	ds_read_b128 v[190:193], v223 offset:6144
	s_waitcnt lgkmcnt(7)
	v_mfma_f32_32x32x16_bf16 v[116:131], v[132:135], v[148:151], v[116:131]
	s_waitcnt lgkmcnt(0)
	s_waitcnt vmcnt(0)
	s_barrier
	v_mfma_f32_32x32x16_bf16 v[100:115], v[140:143], v[148:151], v[100:115]
	v_mfma_f32_32x32x16_bf16 v[84:99], v[132:135], v[162:165], v[84:99]
	v_mfma_f32_32x32x16_bf16 v[68:83], v[140:143], v[162:165], v[68:83]
	v_mfma_f32_32x32x16_bf16 v[52:67], v[132:135], v[178:181], v[52:67]
	v_mfma_f32_32x32x16_bf16 v[36:51], v[140:143], v[178:181], v[36:51]
	v_mfma_f32_32x32x16_bf16 v[20:35], v[132:135], v[186:189], v[20:35]
	v_mfma_f32_32x32x16_bf16 v[4:19], v[140:143], v[186:189], v[4:19]
	v_mfma_f32_32x32x16_bf16 v[116:131], v[136:139], v[152:155], v[116:131]
	v_mfma_f32_32x32x16_bf16 v[100:115], v[144:147], v[152:155], v[100:115]
	v_mfma_f32_32x32x16_bf16 v[84:99], v[136:139], v[174:177], v[84:99]
	v_mfma_f32_32x32x16_bf16 v[68:83], v[144:147], v[174:177], v[68:83]
	v_mfma_f32_32x32x16_bf16 v[52:67], v[136:139], v[182:185], v[52:67]
	v_mfma_f32_32x32x16_bf16 v[36:51], v[144:147], v[182:185], v[36:51]
	v_mfma_f32_32x32x16_bf16 v[20:35], v[136:139], v[190:193], v[20:35]
	v_mfma_f32_32x32x16_bf16 v[4:19], v[144:147], v[190:193], v[4:19]
	v_add_u32_e32 v226, s99, v172
	v_add_u32_e32 v227, s99, v173
	v_add_u32_e32 v228, s99, v171
	v_add_u32_e32 v229, s99, v170
	s_mov_b32 s101, s100
	s_mov_b32 s100, s99
	s_mov_b32 s99, s98
	s_mov_b32 s98, s101
	ds_read_b128 v[132:135], v226 offset:6144
	ds_read_b128 v[136:139], v227 offset:6144
	ds_read_b128 v[140:143], v227 offset:4096
	ds_read_b128 v[144:147], v227 offset:2048
	ds_read_b128 v[148:151], v226
	ds_read_b128 v[152:155], v227
	ds_read_b128 v[162:165], v229 offset:2048
	ds_read_b128 v[174:177], v228
	ds_read_b128 v[178:181], v229
	ds_read_b128 v[182:185], v226 offset:4096
	ds_read_b128 v[186:189], v226 offset:2048
	ds_read_b128 v[190:193], v228 offset:2048
	s_waitcnt lgkmcnt(4)
	v_mfma_f32_32x32x16_bf16 v[116:131], v[174:177], v[148:151], v[116:131]
	s_movk_i32 s0, 0xa00
	s_movk_i32 s11, 0x1400
	s_movk_i32 s14, 0xc00
	s_movk_i32 s16, 0xec00
	s_mov_b32 s17, -1
	s_movk_i32 s18, 0xec20
	s_mov_b32 s19, -1
	s_waitcnt lgkmcnt(0)
	v_mfma_f32_32x32x16_bf16 v[100:115], v[190:193], v[148:151], v[100:115]
	v_add_u32_e32 v148, s2, v168
	s_movk_i32 s20, 0xec40
	s_movk_i32 s2, 0x9e0
	s_mov_b32 s21, -1
	s_movk_i32 s24, 0xec60
	s_movk_i32 s4, 0x9d0
	s_mov_b64 s[22:23], 0x60
	v_mfma_f32_32x32x16_bf16 v[52:67], v[174:177], v[182:185], v[52:67]
	s_mov_b32 s25, -1
	v_mfma_f32_32x32x16_bf16 v[36:51], v[190:193], v[182:185], v[36:51]
	v_mfma_f32_32x32x16_bf16 v[20:35], v[174:177], v[132:135], v[20:35]
	v_mfma_f32_32x32x16_bf16 v[4:19], v[190:193], v[132:135], v[4:19]
	v_mov_b64_e32 v[134:135], s[6:7]
	v_mov_b64_e32 v[132:133], s[8:9]
	v_mfma_f32_32x32x16_bf16 v[84:99], v[174:177], v[186:189], v[84:99]
	v_mfma_f32_32x32x16_bf16 v[68:83], v[190:193], v[186:189], v[68:83]
	v_mfma_f32_32x32x16_bf16 v[116:131], v[178:181], v[152:155], v[116:131]
	v_mfma_f32_32x32x16_bf16 v[100:115], v[162:165], v[152:155], v[100:115]
	s_nop 10
	v_cvt_pk_bf16_f32 v116, v116, v117
	v_cvt_pk_bf16_f32 v117, v118, v119
	v_mfma_f32_32x32x16_bf16 v[52:67], v[178:181], v[140:143], v[52:67]
	v_cvt_pk_bf16_f32 v118, v100, v101
	v_cvt_pk_bf16_f32 v119, v102, v103
	v_mfma_f32_32x32x16_bf16 v[36:51], v[162:165], v[140:143], v[36:51]
	v_or_b32_e32 v140, s3, v169
	v_ashrrev_i32_e32 v141, 31, v140
	v_cmp_gt_i32_e32 vcc, s0, v140
	v_mad_i64_i32 v[142:143], s[0:1], v148, s14, v[132:133]
	v_cmp_gt_i32_e64 s[2:3], s2, v140
	v_cmp_gt_i32_e64 s[4:5], s4, v140
	v_mfma_f32_32x32x16_bf16 v[20:35], v[178:181], v[136:139], v[20:35]
	s_nop 1
	v_cvt_pk_bf16_f32 v52, v52, v53
	v_cvt_pk_bf16_f32 v53, v54, v55
	s_nop 0
	v_cvt_pk_bf16_f32 v54, v36, v37
	v_cvt_pk_bf16_f32 v55, v38, v39
	v_mfma_f32_32x32x16_bf16 v[4:19], v[162:165], v[136:139], v[4:19]
	v_mad_i64_i32 v[138:139], s[0:1], v148, s11, v[134:135]
	v_lshlrev_b64 v[136:137], 1, v[140:141]
	v_mov_b32_e32 v141, v3
	s_movk_i32 s0, 0x9f0
	v_cmp_gt_i32_e64 s[0:1], s0, v140
	v_cvt_pk_bf16_f32 v20, v20, v21
	v_mfma_f32_32x32x16_bf16 v[84:99], v[178:181], v[144:147], v[84:99]
	v_cvt_pk_bf16_f32 v21, v22, v23
	s_nop 3
	v_cvt_pk_bf16_f32 v22, v4, v5
	v_cvt_pk_bf16_f32 v23, v6, v7
	v_mfma_f32_32x32x16_bf16 v[68:83], v[162:165], v[144:147], v[68:83]
	v_lshl_add_u64 v[144:145], v[138:139], 0, v[136:137]
	v_lshlrev_b64 v[138:139], 1, v[140:141]
	v_lshl_add_u64 v[142:143], v[142:143], 0, v[138:139]
	v_lshl_add_u64 v[146:147], v[142:143], 0, s[16:17]
	v_cndmask_b32_e32 v147, v147, v145, vcc
	v_cndmask_b32_e32 v146, v146, v144, vcc
	v_lshl_add_u64 v[100:101], v[144:145], 0, 32
	v_lshl_add_u64 v[102:103], v[142:143], 0, s[18:19]
	global_store_dwordx4 v[146:147], v[116:119], off
	v_cvt_pk_bf16_f32 v84, v84, v85
	v_cvt_pk_bf16_f32 v85, v86, v87
	v_cndmask_b32_e64 v117, v103, v101, s[0:1]
	v_cndmask_b32_e64 v116, v102, v100, s[0:1]
	v_cvt_pk_bf16_f32 v100, v120, v121
	v_cvt_pk_bf16_f32 v101, v122, v123
	v_cvt_pk_bf16_f32 v102, v104, v105
; DI unsigned pack2(float a, float b) { f2_t v = {a, b}; return __builtin_bit_cast(unsigned, __builtin_convertvector(v, bf2_t)); }
;   template <int MF> DI void operator()(f32x16 (&acc)[MF][2], int mb, int nb, int l31, int h) const {
; #pragma unroll
;     for (int mi = 0; mi < MF; ++mi) {
;       const int row = mb + mi * 32 + l31;
; #pragma unroll
;       for (int g4 = 0; g4 < 4; ++g4) {
;         const int col0 = nb + 16 * g4 + 8 * h;
;         u16* dst = (col0 < 2560) ? zhg + (size_t)row * 2560 + col0 : zhy + (size_t)row * 1536 + (col0 - 2560);
;         *(u32x4*)dst = (u32x4){pack2(acc[mi][0][4 * g4], acc[mi][0][4 * g4 + 1]), pack2(acc[mi][0][4 * g4 + 2], acc[mi][0][4 * g4 + 3]),
;                                pack2(acc[mi][1][4 * g4], acc[mi][1][4 * g4 + 1]), pack2(acc[mi][1][4 * g4 + 2], acc[mi][1][4 * g4 + 3])};
;       }
;     }
;   }
	v_cvt_pk_bf16_f32 v103, v106, v107
	global_store_dwordx4 v[116:117], v[100:103], off
	v_cvt_pk_bf16_f32 v86, v68, v69
	v_cvt_pk_bf16_f32 v87, v70, v71
	v_lshl_add_u64 v[100:101], v[144:145], 0, 64
	v_lshl_add_u64 v[102:103], v[142:143], 0, s[20:21]
	v_cndmask_b32_e64 v105, v103, v101, s[2:3]
	v_cndmask_b32_e64 v104, v102, v100, s[2:3]
	v_cvt_pk_bf16_f32 v100, v124, v125
	v_cvt_pk_bf16_f32 v101, v126, v127
	v_cvt_pk_bf16_f32 v102, v108, v109
	v_cvt_pk_bf16_f32 v103, v110, v111
	global_store_dwordx4 v[104:105], v[100:103], off
	s_nop 1
	v_lshl_add_u64 v[100:101], v[144:145], 0, s[22:23]
	v_lshl_add_u64 v[102:103], v[142:143], 0, s[24:25]
	v_cndmask_b32_e64 v105, v103, v101, s[4:5]
	v_cndmask_b32_e64 v104, v102, v100, s[4:5]
	v_cvt_pk_bf16_f32 v100, v128, v129
	v_cvt_pk_bf16_f32 v101, v130, v131
	v_cvt_pk_bf16_f32 v102, v112, v113
	v_cvt_pk_bf16_f32 v103, v114, v115
	global_store_dwordx4 v[104:105], v[100:103], off
	s_nop 1
	v_or_b32_e32 v102, 32, v148
	v_mad_i64_i32 v[100:101], s[12:13], v102, s14, v[132:133]
	v_mad_i64_i32 v[102:103], s[12:13], v102, s11, v[134:135]
	v_lshl_add_u64 v[100:101], v[100:101], 0, v[138:139]
	v_lshl_add_u64 v[102:103], v[102:103], 0, v[136:137]
	v_lshl_add_u64 v[104:105], v[100:101], 0, s[16:17]
	v_cndmask_b32_e32 v105, v105, v103, vcc
	v_cndmask_b32_e32 v104, v104, v102, vcc
	v_lshl_add_u64 v[68:69], v[102:103], 0, 32
	v_lshl_add_u64 v[70:71], v[100:101], 0, s[18:19]
	global_store_dwordx4 v[104:105], v[84:87], off
	s_nop 1
	v_cndmask_b32_e64 v85, v71, v69, s[0:1]
	v_cndmask_b32_e64 v84, v70, v68, s[0:1]
	v_cvt_pk_bf16_f32 v68, v88, v89
	v_cvt_pk_bf16_f32 v69, v90, v91
	v_cvt_pk_bf16_f32 v70, v72, v73
	v_cvt_pk_bf16_f32 v71, v74, v75
	global_store_dwordx4 v[84:85], v[68:71], off
	s_nop 1
	v_lshl_add_u64 v[68:69], v[102:103], 0, 64
	v_lshl_add_u64 v[70:71], v[100:101], 0, s[20:21]
	v_cndmask_b32_e64 v73, v71, v69, s[2:3]
	v_cndmask_b32_e64 v72, v70, v68, s[2:3]
	v_cvt_pk_bf16_f32 v68, v92, v93
	v_cvt_pk_bf16_f32 v69, v94, v95
	v_cvt_pk_bf16_f32 v70, v76, v77
	v_cvt_pk_bf16_f32 v71, v78, v79
	global_store_dwordx4 v[72:73], v[68:71], off
	s_nop 1
	v_lshl_add_u64 v[68:69], v[102:103], 0, s[22:23]
	v_lshl_add_u64 v[70:71], v[100:101], 0, s[24:25]
	v_cndmask_b32_e64 v73, v71, v69, s[4:5]
	v_cndmask_b32_e64 v72, v70, v68, s[4:5]
	v_cvt_pk_bf16_f32 v68, v96, v97
	v_cvt_pk_bf16_f32 v69, v98, v99
	v_cvt_pk_bf16_f32 v70, v80, v81
	v_cvt_pk_bf16_f32 v71, v82, v83
	global_store_dwordx4 v[72:73], v[68:71], off
	s_nop 1
	v_or_b32_e32 v70, 64, v148
	v_mad_i64_i32 v[68:69], s[12:13], v70, s14, v[132:133]
	v_mad_i64_i32 v[70:71], s[12:13], v70, s11, v[134:135]
	v_lshl_add_u64 v[68:69], v[68:69], 0, v[138:139]
	v_lshl_add_u64 v[70:71], v[70:71], 0, v[136:137]
	v_lshl_add_u64 v[72:73], v[68:69], 0, s[16:17]
	v_cndmask_b32_e32 v73, v73, v71, vcc
	v_cndmask_b32_e32 v72, v72, v70, vcc
	v_lshl_add_u64 v[36:37], v[70:71], 0, 32
	v_lshl_add_u64 v[38:39], v[68:69], 0, s[18:19]
	global_store_dwordx4 v[72:73], v[52:55], off
	s_nop 1
	v_cndmask_b32_e64 v53, v39, v37, s[0:1]
	v_cndmask_b32_e64 v52, v38, v36, s[0:1]
	v_cvt_pk_bf16_f32 v36, v56, v57
	v_cvt_pk_bf16_f32 v37, v58, v59
	v_cvt_pk_bf16_f32 v38, v40, v41
	v_cvt_pk_bf16_f32 v39, v42, v43
	global_store_dwordx4 v[52:53], v[36:39], off
	s_nop 1
	v_lshl_add_u64 v[36:37], v[70:71], 0, 64
	v_lshl_add_u64 v[38:39], v[68:69], 0, s[20:21]
	v_cndmask_b32_e64 v41, v39, v37, s[2:3]
	v_cndmask_b32_e64 v40, v38, v36, s[2:3]
	v_cvt_pk_bf16_f32 v36, v60, v61
	v_cvt_pk_bf16_f32 v37, v62, v63
	v_cvt_pk_bf16_f32 v38, v44, v45
	v_cvt_pk_bf16_f32 v39, v46, v47
	global_store_dwordx4 v[40:41], v[36:39], off
	s_nop 1
	v_lshl_add_u64 v[36:37], v[70:71], 0, s[22:23]
	v_lshl_add_u64 v[38:39], v[68:69], 0, s[24:25]
	v_cndmask_b32_e64 v41, v39, v37, s[4:5]
	v_cndmask_b32_e64 v40, v38, v36, s[4:5]
	v_cvt_pk_bf16_f32 v36, v64, v65
	v_cvt_pk_bf16_f32 v37, v66, v67
	v_cvt_pk_bf16_f32 v38, v48, v49
	v_cvt_pk_bf16_f32 v39, v50, v51
	global_store_dwordx4 v[40:41], v[36:39], off
	s_nop 1
	v_or_b32_e32 v38, 0x60, v148
	v_mad_i64_i32 v[36:37], s[12:13], v38, s14, v[132:133]
	v_mad_i64_i32 v[38:39], s[12:13], v38, s11, v[134:135]
	v_lshl_add_u64 v[36:37], v[36:37], 0, v[138:139]
	v_lshl_add_u64 v[38:39], v[38:39], 0, v[136:137]
	v_lshl_add_u64 v[40:41], v[36:37], 0, s[16:17]
	v_cndmask_b32_e32 v41, v41, v39, vcc
	v_cndmask_b32_e32 v40, v40, v38, vcc
	v_lshl_add_u64 v[4:5], v[38:39], 0, 32
	v_lshl_add_u64 v[6:7], v[36:37], 0, s[18:19]
	global_store_dwordx4 v[40:41], v[20:23], off
	s_nop 1
	v_cndmask_b32_e64 v21, v7, v5, s[0:1]
	v_cndmask_b32_e64 v20, v6, v4, s[0:1]
	v_cvt_pk_bf16_f32 v4, v24, v25
	v_cvt_pk_bf16_f32 v5, v26, v27
	v_cvt_pk_bf16_f32 v6, v8, v9
	v_cvt_pk_bf16_f32 v7, v10, v11
	global_store_dwordx4 v[20:21], v[4:7], off
	v_readlane_b32 s0, v252, 40
	s_add_i32 s10, s10, s0
	v_lshl_add_u64 v[4:5], v[38:39], 0, 64
	v_lshl_add_u64 v[6:7], v[36:37], 0, s[20:21]
	v_cndmask_b32_e64 v9, v7, v5, s[2:3]
	v_cndmask_b32_e64 v8, v6, v4, s[2:3]
	v_cvt_pk_bf16_f32 v4, v28, v29
	v_cvt_pk_bf16_f32 v5, v30, v31
	v_cvt_pk_bf16_f32 v6, v12, v13
	v_cvt_pk_bf16_f32 v7, v14, v15
	global_store_dwordx4 v[8:9], v[4:7], off
	s_cmpk_gt_i32 s10, 0x10ff
	v_readlane_b32 s1, v252, 41
	v_lshl_add_u64 v[4:5], v[38:39], 0, s[22:23]
	v_lshl_add_u64 v[6:7], v[36:37], 0, s[24:25]
	v_cndmask_b32_e64 v9, v7, v5, s[4:5]
	v_cndmask_b32_e64 v8, v6, v4, s[4:5]
	v_cvt_pk_bf16_f32 v4, v32, v33
	v_cvt_pk_bf16_f32 v5, v34, v35
	v_cvt_pk_bf16_f32 v6, v16, v17
	v_cvt_pk_bf16_f32 v7, v18, v19
	global_store_dwordx4 v[8:9], v[4:7], off
	s_cbranch_scc0 .LBB0_953
